# hand-written conv ported to the early and seam prompt memory-attention unit instances
# speedup vs baseline: 1.0239x; 1.0111x over previous
; DI v2u pack4(f32x4 a) { v2u w; w.x = cvtpk(a[0], a[1]); w.y = cvtpk(a[2], a[3]); return w; }
; DI f32x4 unpack4(v2u w) { return (f32x4){bflo(w.x), bfhi(w.x), bflo(w.y), bfhi(w.y)}; }
; DI void unit_memattn(int u, const bf16* __restrict__ MQ, const bf16* __restrict__ MK, const bf16* __restrict__ MV, const bf16* __restrict__ G, bf16* __restrict__ MIX, const bf16* __restrict__ CB, const bf16* __restrict__ U, const float* __restrict__ convw, ...
;     ...
;     const int b = u >> 7, hm = (u >> 5) & 3, qb = u & 31;
;     const long goff0 = ((long)b * 256) * 256 + hm * 64;
;     v4u fk[4], fv[4], gv[4];
; #pragma unroll
;     for (int i = 0; i < 4; ++i) { const int id = tid + NT * i, j = id >> 3, ch = id & 7;
;         fk[i] = *(const v4u*)(MK + goff0 + (long)j * 256 + ch * 8); fv[i] = *(const v4u*)(MV + goff0 + (long)j * 256 + ch * 8);
;         gv[i] = *(const v4u*)(G + ((size_t)b * SEQ + qb * 256 + j) * D + 768 + hm * 64 + ch * 8); }
;     {   const int c4 = hm * 64 + (tid & 15) * 4;
;         const f32x4 w0 = *(const f32x4*)(convw + c4), w1 = *(const f32x4*)(convw + 256 + c4), w2 = *(const f32x4*)(convw + 512 + c4);
; #pragma unroll 4
;         for (int rl = tid >> 4; rl < 256; rl += NT / 16) { const size_t r2 = (size_t)b * SEQ + qb * 256 + rl; const int t = (int)(r2 & (SEQ - 1));
;             const f32x4 cb = unpack4(*(const v2u*)(CB + r2 * 256 + c4)), u0 = unpack4(*(const v2u*)(U + r2 * 256 + c4));
;             f32x4 u1 = (f32x4){0.f, 0.f, 0.f, 0.f}, u2 = u1;
;             if (t >= 1) u1 = unpack4(*(const v2u*)(U + (r2 - 1) * 256 + c4));
;             if (t >= 2) u2 = unpack4(*(const v2u*)(U + (r2 - 2) * 256 + c4));
;             const f32x4 gg = unpack4(*(const v2u*)(G + r2 * D + c4));
;             *(v2u*)(MIX + r2 * D + c4) = pack4(cb * (w0 * u2 + w1 * u1 + w2 * u0) * gg); }
.LBB0_501:
	s_or_b64 exec, exec, s[2:3]
	s_waitcnt lgkmcnt(0)
	s_barrier
	ds_read_b32 v2, v1
	s_xor_b64 s[10:11], s[10:11], -1
	s_waitcnt lgkmcnt(0)
	v_readfirstlane_b32 s3, v2
	s_cmpk_gt_i32 s3, 0xff
	s_cbranch_scc1 .LBB0_496
	s_ashr_i32 s12, s3, 7
	s_lshl_b32 s2, s3, 1
	s_ashr_i32 s13, s12, 31
	s_and_b32 s2, s2, 0xc0
	s_lshl_b64 s[14:15], s[12:13], 17
	s_lshl_b32 s4, s2, 1
	s_or_b32 s14, s14, s4
	v_mov_b32_e32 v153, v182
	v_mov_b32_e32 v152, v0
	s_add_u32 s16, s64, s14
	s_addc_u32 s17, s65, s15
	v_lshlrev_b32_e32 v2, 3, v152
	v_and_b32_e32 v2, 56, v2
	s_add_u32 s14, s66, s14
	v_lshlrev_b32_e32 v132, 1, v2
	v_mov_b32_e32 v133, v3
	s_addc_u32 s15, s67, s15
	s_lshl_b32 s3, s3, 8
	v_lshl_add_u64 v[28:29], s[16:17], 0, v[132:133]
	s_lshl_b64 s[16:17], s[12:13], 13
	s_and_b32 s13, s3, 0x1f00
	v_ashrrev_i32_e32 v142, 3, v152
	v_lshl_add_u64 v[32:33], s[14:15], 0, v[132:133]
	s_or_b32 s14, s16, s13
	s_mov_b32 s15, s17
	v_ashrrev_i32_e32 v143, 31, v142
	v_lshlrev_b64 v[4:5], 9, v[142:143]
	v_lshl_add_u64 v[12:13], s[14:15], 0, v[142:143]
	v_add_u32_e32 v143, 0x200, v152
	v_ashrrev_i32_e32 v144, 3, v143
	v_ashrrev_i32_e32 v145, 31, v144
	v_lshl_add_u64 v[18:19], s[14:15], 0, v[144:145]
	v_lshlrev_b64 v[140:141], 11, v[12:13]
	v_lshlrev_b64 v[138:139], 11, v[18:19]
	v_lshl_add_u64 v[12:13], s[24:25], 0, v[140:141]
	v_lshlrev_b64 v[16:17], 9, v[144:145]
	v_lshl_add_u64 v[18:19], s[24:25], 0, v[138:139]
	v_add_u32_e32 v145, 0x400, v152
	v_lshl_add_u64 v[12:13], v[12:13], 0, s[4:5]
	v_lshl_add_u64 v[18:19], v[18:19], 0, s[4:5]
	v_ashrrev_i32_e32 v146, 3, v145
	v_lshl_add_u64 v[6:7], v[28:29], 0, v[4:5]
	v_lshl_add_u64 v[8:9], v[32:33], 0, v[4:5]
	v_lshl_add_u64 v[12:13], v[12:13], 0, v[132:133]
	v_lshl_add_u64 v[14:15], v[28:29], 0, v[16:17]
	v_lshl_add_u64 v[16:17], v[32:33], 0, v[16:17]
	v_lshl_add_u64 v[20:21], v[18:19], 0, v[132:133]
	v_ashrrev_i32_e32 v147, 31, v146
	global_load_dwordx4 v[4:7], v[6:7], off
	s_nop 0
	global_load_dwordx4 v[8:11], v[8:9], off
	s_nop 0
	global_load_dwordx4 v[80:83], v[12:13], off offset:1536
	s_nop 0
	global_load_dwordx4 v[12:15], v[14:15], off
	s_nop 0
	global_load_dwordx4 v[16:19], v[16:17], off
	s_nop 0
	global_load_dwordx4 v[76:79], v[20:21], off offset:1536
	v_lshlrev_b64 v[20:21], 9, v[146:147]
	v_lshl_add_u64 v[30:31], s[14:15], 0, v[146:147]
	v_add_u32_e32 v147, 0x600, v152
	v_ashrrev_i32_e32 v148, 3, v147
	v_ashrrev_i32_e32 v149, 31, v148
	v_lshlrev_b64 v[34:35], 9, v[148:149]
	v_lshl_add_u64 v[22:23], v[28:29], 0, v[20:21]
	v_lshl_add_u64 v[24:25], v[32:33], 0, v[20:21]
	v_lshlrev_b64 v[136:137], 11, v[30:31]
	v_lshl_add_u64 v[28:29], v[28:29], 0, v[34:35]
	v_lshl_add_u64 v[32:33], v[32:33], 0, v[34:35]
	v_lshl_add_u64 v[34:35], s[14:15], 0, v[148:149]
	v_lshl_add_u64 v[30:31], s[24:25], 0, v[136:137]
	v_lshlrev_b64 v[134:135], 11, v[34:35]
	v_lshl_add_u64 v[30:31], v[30:31], 0, s[4:5]
	v_lshl_add_u64 v[34:35], s[24:25], 0, v[134:135]
	v_lshl_add_u64 v[30:31], v[30:31], 0, v[132:133]
	v_lshl_add_u64 v[34:35], v[34:35], 0, s[4:5]
	global_load_dwordx4 v[20:23], v[22:23], off
	s_nop 0
	global_load_dwordx4 v[24:27], v[24:25], off
	s_nop 0
	global_load_dwordx4 v[72:75], v[30:31], off offset:1536
	s_nop 0
	global_load_dwordx4 v[28:31], v[28:29], off
	v_lshl_add_u64 v[36:37], v[34:35], 0, v[132:133]
	global_load_dwordx4 v[32:35], v[32:33], off
	s_nop 0
	global_load_dwordx4 v[68:71], v[36:37], off offset:1536
	v_ashrrev_i32_e32 v60, 4, v152
	s_movk_i32 s3, 0x100
	v_cmp_gt_i32_e32 vcc, s3, v60
	s_and_saveexec_b64 s[14:15], vcc
	s_cbranch_execz .LBB0_530
	v_lshlrev_b32_e32 v2, 2, v152
	v_and_or_b32 v2, v2, 60, s2
	v_readlane_b32 s40, v247, 25
	v_readlane_b32 s41, v247, 26
	v_readlane_b32 s42, v247, 27
	v_readlane_b32 s43, v247, 28
	v_readlane_b32 s44, v247, 29
	v_readlane_b32 s45, v247, 30
	v_readlane_b32 s46, v247, 31
	v_readlane_b32 s47, v247, 32
	v_readlane_b32 s48, v247, 33
	v_readlane_b32 s49, v247, 34
	v_readlane_b32 s50, v247, 35
	v_readlane_b32 s51, v247, 36
	v_readlane_b32 s52, v247, 37
	v_readlane_b32 s53, v247, 38
	v_readlane_b32 s54, v247, 39
	v_readlane_b32 s55, v247, 40
	v_lshlrev_b32_e32 v104, 2, v2
	v_mov_b32_e32 v118, 0
	s_lshl_b32 s39, s12, 13
	s_or_b32 s39, s39, s13
	global_load_dwordx4 v[36:39], v104, s[44:45]
	global_load_dwordx4 v[40:43], v104, s[44:45] offset:1024
	global_load_dwordx4 v[44:47], v104, s[44:45] offset:2048
	s_lshl_b32 s16, s39, 9
	s_add_u32 s16, s16, 0x3400000
	s_add_u32 s16, s82, s16
	s_addc_u32 s17, s83, 0
	s_add_u32 s18, s16, 0xa00000
	s_addc_u32 s19, s17, 0
	s_lshl_b32 s20, s39, 11
	s_add_u32 s20, s20, 0x8800000
	s_add_u32 s20, s82, s20
	s_addc_u32 s21, s83, 0
	s_add_u32 s2, s20, 0x5800000
	s_addc_u32 s3, s21, 0
	v_lshlrev_b32_e32 v2, 1, v2
	v_add_u32_e32 v107, s13, v60
	v_lshl_add_u32 v104, v60, 9, v2
	v_lshl_add_u32 v105, v60, 11, v2
	v_mov_b32_e32 v106, v105
	global_load_dwordx2 v[48:49], v104, s[16:17]
	global_load_dwordx2 v[50:51], v104, s[18:19]
	global_load_dwordx2 v[52:53], v104, s[18:19] offset:-512
	global_load_dwordx2 v[54:55], v104, s[18:19] offset:-1024
	global_load_dwordx2 v[56:57], v105, s[20:21]
	v_add_u32_e32 v104, 0x4000, v104
	v_add_u32_e32 v105, 0x10000, v105
	global_load_dwordx2 v[58:59], v104, s[16:17]
	global_load_dwordx2 v[60:61], v104, s[18:19]
	global_load_dwordx2 v[62:63], v104, s[18:19] offset:-512
	global_load_dwordx2 v[64:65], v104, s[18:19] offset:-1024
	global_load_dwordx2 v[66:67], v105, s[20:21]
	v_add_u32_e32 v104, 0x4000, v104
	v_add_u32_e32 v105, 0x10000, v105
	global_load_dwordx2 v[84:85], v104, s[16:17]
	global_load_dwordx2 v[86:87], v104, s[18:19]
	global_load_dwordx2 v[88:89], v104, s[18:19] offset:-512
	global_load_dwordx2 v[90:91], v104, s[18:19] offset:-1024
	global_load_dwordx2 v[92:93], v105, s[20:21]
	v_add_u32_e32 v104, 0x4000, v104
	v_add_u32_e32 v105, 0x10000, v105
	global_load_dwordx2 v[94:95], v104, s[16:17]
	global_load_dwordx2 v[96:97], v104, s[18:19]
	global_load_dwordx2 v[98:99], v104, s[18:19] offset:-512
	global_load_dwordx2 v[100:101], v104, s[18:19] offset:-1024
	global_load_dwordx2 v[102:103], v105, s[20:21]
	v_add_u32_e32 v104, 0x4000, v104
	v_add_u32_e32 v105, 0x10000, v105
	s_waitcnt vmcnt(15)
; DI v2u pack4(f32x4 a) { v2u w; w.x = cvtpk(a[0], a[1]); w.y = cvtpk(a[2], a[3]); return w; }
; DI f32x4 unpack4(v2u w) { return (f32x4){bflo(w.x), bfhi(w.x), bflo(w.y), bfhi(w.y)}; }
; DI void unit_memattn(int u, const bf16* __restrict__ MQ, const bf16* __restrict__ MK, const bf16* __restrict__ MV, const bf16* __restrict__ G, bf16* __restrict__ MIX, const bf16* __restrict__ CB, const bf16* __restrict__ U, const float* __restrict__ convw, ...
;     ...
;         for (int rl = tid >> 4; rl < 256; rl += NT / 16) { const size_t r2 = (size_t)b * SEQ + qb * 256 + rl; const int t = (int)(r2 & (SEQ - 1));
;             const f32x4 cb = unpack4(*(const v2u*)(CB + r2 * 256 + c4)), u0 = unpack4(*(const v2u*)(U + r2 * 256 + c4));
;             f32x4 u1 = (f32x4){0.f, 0.f, 0.f, 0.f}, u2 = u1;
;             if (t >= 1) u1 = unpack4(*(const v2u*)(U + (r2 - 1) * 256 + c4));
;             if (t >= 2) u2 = unpack4(*(const v2u*)(U + (r2 - 2) * 256 + c4));
;             const f32x4 gg = unpack4(*(const v2u*)(G + r2 * D + c4));
;             *(v2u*)(MIX + r2 * D + c4) = pack4(cb * (w0 * u2 + w1 * u1 + w2 * u0) * gg); }
	v_cmp_ne_u32_e32 vcc, 0, v107
	s_nop 1
	v_cndmask_b32_e32 v52, v118, v52, vcc
	v_cndmask_b32_e32 v53, v118, v53, vcc
	v_cmp_lt_u32_e32 vcc, 1, v107
	s_nop 1
	v_cndmask_b32_e32 v54, v118, v54, vcc
	v_cndmask_b32_e32 v55, v118, v55, vcc
	v_lshlrev_b32_e32 v108, 16, v54
	v_and_b32_e32 v109, 0xffff0000, v54
	v_lshlrev_b32_e32 v110, 16, v55
	v_and_b32_e32 v111, 0xffff0000, v55
	v_pk_mul_f32 v[114:115], v[38:39], v[110:111]
	v_pk_mul_f32 v[112:113], v[36:37], v[108:109]
	v_lshlrev_b32_e32 v108, 16, v52
	v_and_b32_e32 v109, 0xffff0000, v52
	v_lshlrev_b32_e32 v110, 16, v53
	v_and_b32_e32 v111, 0xffff0000, v53
	v_pk_fma_f32 v[112:113], v[40:41], v[108:109], v[112:113]
	v_pk_fma_f32 v[114:115], v[42:43], v[110:111], v[114:115]
	v_lshlrev_b32_e32 v108, 16, v50
	v_and_b32_e32 v109, 0xffff0000, v50
	v_lshlrev_b32_e32 v110, 16, v51
	v_and_b32_e32 v111, 0xffff0000, v51
	v_pk_fma_f32 v[114:115], v[46:47], v[110:111], v[114:115]
	v_pk_fma_f32 v[112:113], v[44:45], v[108:109], v[112:113]
	v_lshlrev_b32_e32 v108, 16, v48
	v_and_b32_e32 v109, 0xffff0000, v48
	v_lshlrev_b32_e32 v110, 16, v49
	v_and_b32_e32 v111, 0xffff0000, v49
	v_pk_mul_f32 v[112:113], v[112:113], v[108:109]
	v_pk_mul_f32 v[114:115], v[114:115], v[110:111]
	v_lshlrev_b32_e32 v108, 16, v56
	v_and_b32_e32 v109, 0xffff0000, v56
	v_lshlrev_b32_e32 v110, 16, v57
	v_and_b32_e32 v111, 0xffff0000, v57
	v_pk_mul_f32 v[114:115], v[114:115], v[110:111]
	v_pk_mul_f32 v[112:113], v[112:113], v[108:109]
	s_nop 0
	v_cvt_pk_bf16_f32 v116, v112, v113
	v_cvt_pk_bf16_f32 v117, v114, v115
	global_load_dwordx2 v[48:49], v104, s[16:17]
	global_load_dwordx2 v[50:51], v104, s[18:19]
	global_load_dwordx2 v[52:53], v104, s[18:19] offset:-512
	global_load_dwordx2 v[54:55], v104, s[18:19] offset:-1024
	global_load_dwordx2 v[56:57], v105, s[20:21]
	v_add_u32_e32 v104, 0x4000, v104
	v_add_u32_e32 v105, 0x10000, v105
	global_store_dwordx2 v106, v[116:117], s[2:3]
	v_add_u32_e32 v106, 0x10000, v106
	s_waitcnt vmcnt(16)
	v_lshlrev_b32_e32 v108, 16, v64
	v_and_b32_e32 v109, 0xffff0000, v64
	v_lshlrev_b32_e32 v110, 16, v65
	v_and_b32_e32 v111, 0xffff0000, v65
	v_pk_mul_f32 v[114:115], v[38:39], v[110:111]
	v_pk_mul_f32 v[112:113], v[36:37], v[108:109]
	v_lshlrev_b32_e32 v108, 16, v62
	v_and_b32_e32 v109, 0xffff0000, v62
	v_lshlrev_b32_e32 v110, 16, v63
	v_and_b32_e32 v111, 0xffff0000, v63
	v_pk_fma_f32 v[112:113], v[40:41], v[108:109], v[112:113]
	v_pk_fma_f32 v[114:115], v[42:43], v[110:111], v[114:115]
	v_lshlrev_b32_e32 v108, 16, v60
	v_and_b32_e32 v109, 0xffff0000, v60
	v_lshlrev_b32_e32 v110, 16, v61
	v_and_b32_e32 v111, 0xffff0000, v61
	v_pk_fma_f32 v[114:115], v[46:47], v[110:111], v[114:115]
	v_pk_fma_f32 v[112:113], v[44:45], v[108:109], v[112:113]
	v_lshlrev_b32_e32 v108, 16, v58
	v_and_b32_e32 v109, 0xffff0000, v58
	v_lshlrev_b32_e32 v110, 16, v59
	v_and_b32_e32 v111, 0xffff0000, v59
	v_pk_mul_f32 v[112:113], v[112:113], v[108:109]
	v_pk_mul_f32 v[114:115], v[114:115], v[110:111]
	v_lshlrev_b32_e32 v108, 16, v66
	v_and_b32_e32 v109, 0xffff0000, v66
	v_lshlrev_b32_e32 v110, 16, v67
	v_and_b32_e32 v111, 0xffff0000, v67
	v_pk_mul_f32 v[114:115], v[114:115], v[110:111]
	v_pk_mul_f32 v[112:113], v[112:113], v[108:109]
	s_nop 0
	v_cvt_pk_bf16_f32 v116, v112, v113
	v_cvt_pk_bf16_f32 v117, v114, v115
	global_load_dwordx2 v[58:59], v104, s[16:17]
	global_load_dwordx2 v[60:61], v104, s[18:19]
	global_load_dwordx2 v[62:63], v104, s[18:19] offset:-512
	global_load_dwordx2 v[64:65], v104, s[18:19] offset:-1024
	global_load_dwordx2 v[66:67], v105, s[20:21]
	v_add_u32_e32 v104, 0x4000, v104
	v_add_u32_e32 v105, 0x10000, v105
	global_store_dwordx2 v106, v[116:117], s[2:3]
	v_add_u32_e32 v106, 0x10000, v106
	s_waitcnt vmcnt(17)
	v_lshlrev_b32_e32 v108, 16, v90
	v_and_b32_e32 v109, 0xffff0000, v90
	v_lshlrev_b32_e32 v110, 16, v91
	v_and_b32_e32 v111, 0xffff0000, v91
	v_pk_mul_f32 v[114:115], v[38:39], v[110:111]
	v_pk_mul_f32 v[112:113], v[36:37], v[108:109]
	v_lshlrev_b32_e32 v108, 16, v88
	v_and_b32_e32 v109, 0xffff0000, v88
	v_lshlrev_b32_e32 v110, 16, v89
	v_and_b32_e32 v111, 0xffff0000, v89
	v_pk_fma_f32 v[112:113], v[40:41], v[108:109], v[112:113]
	v_pk_fma_f32 v[114:115], v[42:43], v[110:111], v[114:115]
	v_lshlrev_b32_e32 v108, 16, v86
	v_and_b32_e32 v109, 0xffff0000, v86
	v_lshlrev_b32_e32 v110, 16, v87
	v_and_b32_e32 v111, 0xffff0000, v87
	v_pk_fma_f32 v[114:115], v[46:47], v[110:111], v[114:115]
	v_pk_fma_f32 v[112:113], v[44:45], v[108:109], v[112:113]
	v_lshlrev_b32_e32 v108, 16, v84
	v_and_b32_e32 v109, 0xffff0000, v84
	v_lshlrev_b32_e32 v110, 16, v85
	v_and_b32_e32 v111, 0xffff0000, v85
	v_pk_mul_f32 v[112:113], v[112:113], v[108:109]
	v_pk_mul_f32 v[114:115], v[114:115], v[110:111]
	v_lshlrev_b32_e32 v108, 16, v92
	v_and_b32_e32 v109, 0xffff0000, v92
	v_lshlrev_b32_e32 v110, 16, v93
	v_and_b32_e32 v111, 0xffff0000, v93
	v_pk_mul_f32 v[114:115], v[114:115], v[110:111]
	v_pk_mul_f32 v[112:113], v[112:113], v[108:109]
	s_nop 0
	v_cvt_pk_bf16_f32 v116, v112, v113
	v_cvt_pk_bf16_f32 v117, v114, v115
	global_load_dwordx2 v[84:85], v104, s[16:17]
	global_load_dwordx2 v[86:87], v104, s[18:19]
	global_load_dwordx2 v[88:89], v104, s[18:19] offset:-512
	global_load_dwordx2 v[90:91], v104, s[18:19] offset:-1024
	global_load_dwordx2 v[92:93], v105, s[20:21]
	v_add_u32_e32 v104, 0x4000, v104
	v_add_u32_e32 v105, 0x10000, v105
	global_store_dwordx2 v106, v[116:117], s[2:3]
	v_add_u32_e32 v106, 0x10000, v106
	s_waitcnt vmcnt(18)
; DI v2u pack4(f32x4 a) { v2u w; w.x = cvtpk(a[0], a[1]); w.y = cvtpk(a[2], a[3]); return w; }
; DI f32x4 unpack4(v2u w) { return (f32x4){bflo(w.x), bfhi(w.x), bflo(w.y), bfhi(w.y)}; }
; DI void unit_memattn(int u, const bf16* __restrict__ MQ, const bf16* __restrict__ MK, const bf16* __restrict__ MV, const bf16* __restrict__ G, bf16* __restrict__ MIX, const bf16* __restrict__ CB, const bf16* __restrict__ U, const float* __restrict__ convw, ...
;     ...
;         for (int rl = tid >> 4; rl < 256; rl += NT / 16) { const size_t r2 = (size_t)b * SEQ + qb * 256 + rl; const int t = (int)(r2 & (SEQ - 1));
;             const f32x4 cb = unpack4(*(const v2u*)(CB + r2 * 256 + c4)), u0 = unpack4(*(const v2u*)(U + r2 * 256 + c4));
;             f32x4 u1 = (f32x4){0.f, 0.f, 0.f, 0.f}, u2 = u1;
;             if (t >= 1) u1 = unpack4(*(const v2u*)(U + (r2 - 1) * 256 + c4));
;             if (t >= 2) u2 = unpack4(*(const v2u*)(U + (r2 - 2) * 256 + c4));
;             const f32x4 gg = unpack4(*(const v2u*)(G + r2 * D + c4));
;             *(v2u*)(MIX + r2 * D + c4) = pack4(cb * (w0 * u2 + w1 * u1 + w2 * u0) * gg); }
	v_lshlrev_b32_e32 v108, 16, v100
	v_and_b32_e32 v109, 0xffff0000, v100
	v_lshlrev_b32_e32 v110, 16, v101
	v_and_b32_e32 v111, 0xffff0000, v101
	v_pk_mul_f32 v[114:115], v[38:39], v[110:111]
	v_pk_mul_f32 v[112:113], v[36:37], v[108:109]
	v_lshlrev_b32_e32 v108, 16, v98
	v_and_b32_e32 v109, 0xffff0000, v98
	v_lshlrev_b32_e32 v110, 16, v99
	v_and_b32_e32 v111, 0xffff0000, v99
	v_pk_fma_f32 v[112:113], v[40:41], v[108:109], v[112:113]
	v_pk_fma_f32 v[114:115], v[42:43], v[110:111], v[114:115]
	v_lshlrev_b32_e32 v108, 16, v96
	v_and_b32_e32 v109, 0xffff0000, v96
	v_lshlrev_b32_e32 v110, 16, v97
	v_and_b32_e32 v111, 0xffff0000, v97
	v_pk_fma_f32 v[114:115], v[46:47], v[110:111], v[114:115]
	v_pk_fma_f32 v[112:113], v[44:45], v[108:109], v[112:113]
	v_lshlrev_b32_e32 v108, 16, v94
	v_and_b32_e32 v109, 0xffff0000, v94
	v_lshlrev_b32_e32 v110, 16, v95
	v_and_b32_e32 v111, 0xffff0000, v95
	v_pk_mul_f32 v[112:113], v[112:113], v[108:109]
	v_pk_mul_f32 v[114:115], v[114:115], v[110:111]
	v_lshlrev_b32_e32 v108, 16, v102
	v_and_b32_e32 v109, 0xffff0000, v102
	v_lshlrev_b32_e32 v110, 16, v103
	v_and_b32_e32 v111, 0xffff0000, v103
	v_pk_mul_f32 v[114:115], v[114:115], v[110:111]
	v_pk_mul_f32 v[112:113], v[112:113], v[108:109]
	s_nop 0
	v_cvt_pk_bf16_f32 v116, v112, v113
	v_cvt_pk_bf16_f32 v117, v114, v115
	global_load_dwordx2 v[94:95], v104, s[16:17]
	global_load_dwordx2 v[96:97], v104, s[18:19]
	global_load_dwordx2 v[98:99], v104, s[18:19] offset:-512
	global_load_dwordx2 v[100:101], v104, s[18:19] offset:-1024
	global_load_dwordx2 v[102:103], v105, s[20:21]
	global_store_dwordx2 v106, v[116:117], s[2:3]
	v_add_u32_e32 v106, 0x10000, v106
	s_waitcnt vmcnt(19)
	v_lshlrev_b32_e32 v108, 16, v54
	v_and_b32_e32 v109, 0xffff0000, v54
	v_lshlrev_b32_e32 v110, 16, v55
	v_and_b32_e32 v111, 0xffff0000, v55
	v_pk_mul_f32 v[114:115], v[38:39], v[110:111]
	v_pk_mul_f32 v[112:113], v[36:37], v[108:109]
	v_lshlrev_b32_e32 v108, 16, v52
	v_and_b32_e32 v109, 0xffff0000, v52
	v_lshlrev_b32_e32 v110, 16, v53
	v_and_b32_e32 v111, 0xffff0000, v53
	v_pk_fma_f32 v[112:113], v[40:41], v[108:109], v[112:113]
	v_pk_fma_f32 v[114:115], v[42:43], v[110:111], v[114:115]
	v_lshlrev_b32_e32 v108, 16, v50
	v_and_b32_e32 v109, 0xffff0000, v50
	v_lshlrev_b32_e32 v110, 16, v51
	v_and_b32_e32 v111, 0xffff0000, v51
	v_pk_fma_f32 v[114:115], v[46:47], v[110:111], v[114:115]
	v_pk_fma_f32 v[112:113], v[44:45], v[108:109], v[112:113]
	v_lshlrev_b32_e32 v108, 16, v48
	v_and_b32_e32 v109, 0xffff0000, v48
	v_lshlrev_b32_e32 v110, 16, v49
	v_and_b32_e32 v111, 0xffff0000, v49
	v_pk_mul_f32 v[112:113], v[112:113], v[108:109]
	v_pk_mul_f32 v[114:115], v[114:115], v[110:111]
	v_lshlrev_b32_e32 v108, 16, v56
	v_and_b32_e32 v109, 0xffff0000, v56
	v_lshlrev_b32_e32 v110, 16, v57
	v_and_b32_e32 v111, 0xffff0000, v57
	v_pk_mul_f32 v[114:115], v[114:115], v[110:111]
	v_pk_mul_f32 v[112:113], v[112:113], v[108:109]
	s_nop 0
	v_cvt_pk_bf16_f32 v116, v112, v113
	v_cvt_pk_bf16_f32 v117, v114, v115
	global_store_dwordx2 v106, v[116:117], s[2:3]
	v_add_u32_e32 v106, 0x10000, v106
	s_waitcnt vmcnt(14)
; DI v2u pack4(f32x4 a) { v2u w; w.x = cvtpk(a[0], a[1]); w.y = cvtpk(a[2], a[3]); return w; }
; DI f32x4 unpack4(v2u w) { return (f32x4){bflo(w.x), bfhi(w.x), bflo(w.y), bfhi(w.y)}; }
; DI void unit_memattn(int u, const bf16* __restrict__ MQ, const bf16* __restrict__ MK, const bf16* __restrict__ MV, const bf16* __restrict__ G, bf16* __restrict__ MIX, const bf16* __restrict__ CB, const bf16* __restrict__ U, const float* __restrict__ convw, ...
;     ...
;         for (int rl = tid >> 4; rl < 256; rl += NT / 16) { const size_t r2 = (size_t)b * SEQ + qb * 256 + rl; const int t = (int)(r2 & (SEQ - 1));
;             const f32x4 cb = unpack4(*(const v2u*)(CB + r2 * 256 + c4)), u0 = unpack4(*(const v2u*)(U + r2 * 256 + c4));
;             f32x4 u1 = (f32x4){0.f, 0.f, 0.f, 0.f}, u2 = u1;
;             if (t >= 1) u1 = unpack4(*(const v2u*)(U + (r2 - 1) * 256 + c4));
;             if (t >= 2) u2 = unpack4(*(const v2u*)(U + (r2 - 2) * 256 + c4));
;             const f32x4 gg = unpack4(*(const v2u*)(G + r2 * D + c4));
;             *(v2u*)(MIX + r2 * D + c4) = pack4(cb * (w0 * u2 + w1 * u1 + w2 * u0) * gg); }
	v_lshlrev_b32_e32 v108, 16, v64
	v_and_b32_e32 v109, 0xffff0000, v64
	v_lshlrev_b32_e32 v110, 16, v65
	v_and_b32_e32 v111, 0xffff0000, v65
	v_pk_mul_f32 v[114:115], v[38:39], v[110:111]
	v_pk_mul_f32 v[112:113], v[36:37], v[108:109]
	v_lshlrev_b32_e32 v108, 16, v62
	v_and_b32_e32 v109, 0xffff0000, v62
	v_lshlrev_b32_e32 v110, 16, v63
	v_and_b32_e32 v111, 0xffff0000, v63
	v_pk_fma_f32 v[112:113], v[40:41], v[108:109], v[112:113]
	v_pk_fma_f32 v[114:115], v[42:43], v[110:111], v[114:115]
	v_lshlrev_b32_e32 v108, 16, v60
	v_and_b32_e32 v109, 0xffff0000, v60
	v_lshlrev_b32_e32 v110, 16, v61
	v_and_b32_e32 v111, 0xffff0000, v61
	v_pk_fma_f32 v[114:115], v[46:47], v[110:111], v[114:115]
	v_pk_fma_f32 v[112:113], v[44:45], v[108:109], v[112:113]
	v_lshlrev_b32_e32 v108, 16, v58
	v_and_b32_e32 v109, 0xffff0000, v58
	v_lshlrev_b32_e32 v110, 16, v59
	v_and_b32_e32 v111, 0xffff0000, v59
	v_pk_mul_f32 v[112:113], v[112:113], v[108:109]
	v_pk_mul_f32 v[114:115], v[114:115], v[110:111]
	v_lshlrev_b32_e32 v108, 16, v66
	v_and_b32_e32 v109, 0xffff0000, v66
	v_lshlrev_b32_e32 v110, 16, v67
	v_and_b32_e32 v111, 0xffff0000, v67
	v_pk_mul_f32 v[114:115], v[114:115], v[110:111]
	v_pk_mul_f32 v[112:113], v[112:113], v[108:109]
	s_nop 0
	v_cvt_pk_bf16_f32 v116, v112, v113
	v_cvt_pk_bf16_f32 v117, v114, v115
	global_store_dwordx2 v106, v[116:117], s[2:3]
	v_add_u32_e32 v106, 0x10000, v106
	s_waitcnt vmcnt(9)
	v_lshlrev_b32_e32 v108, 16, v90
	v_and_b32_e32 v109, 0xffff0000, v90
	v_lshlrev_b32_e32 v110, 16, v91
	v_and_b32_e32 v111, 0xffff0000, v91
	v_pk_mul_f32 v[114:115], v[38:39], v[110:111]
	v_pk_mul_f32 v[112:113], v[36:37], v[108:109]
	v_lshlrev_b32_e32 v108, 16, v88
	v_and_b32_e32 v109, 0xffff0000, v88
	v_lshlrev_b32_e32 v110, 16, v89
	v_and_b32_e32 v111, 0xffff0000, v89
	v_pk_fma_f32 v[112:113], v[40:41], v[108:109], v[112:113]
	v_pk_fma_f32 v[114:115], v[42:43], v[110:111], v[114:115]
	v_lshlrev_b32_e32 v108, 16, v86
	v_and_b32_e32 v109, 0xffff0000, v86
	v_lshlrev_b32_e32 v110, 16, v87
	v_and_b32_e32 v111, 0xffff0000, v87
	v_pk_fma_f32 v[114:115], v[46:47], v[110:111], v[114:115]
	v_pk_fma_f32 v[112:113], v[44:45], v[108:109], v[112:113]
	v_lshlrev_b32_e32 v108, 16, v84
	v_and_b32_e32 v109, 0xffff0000, v84
	v_lshlrev_b32_e32 v110, 16, v85
	v_and_b32_e32 v111, 0xffff0000, v85
	v_pk_mul_f32 v[112:113], v[112:113], v[108:109]
	v_pk_mul_f32 v[114:115], v[114:115], v[110:111]
	v_lshlrev_b32_e32 v108, 16, v92
	v_and_b32_e32 v109, 0xffff0000, v92
	v_lshlrev_b32_e32 v110, 16, v93
	v_and_b32_e32 v111, 0xffff0000, v93
	v_pk_mul_f32 v[114:115], v[114:115], v[110:111]
	v_pk_mul_f32 v[112:113], v[112:113], v[108:109]
	s_nop 0
	v_cvt_pk_bf16_f32 v116, v112, v113
	v_cvt_pk_bf16_f32 v117, v114, v115
	global_store_dwordx2 v106, v[116:117], s[2:3]
	v_add_u32_e32 v106, 0x10000, v106
	s_waitcnt vmcnt(4)
	v_lshlrev_b32_e32 v108, 16, v100
	v_and_b32_e32 v109, 0xffff0000, v100
	v_lshlrev_b32_e32 v110, 16, v101
	v_and_b32_e32 v111, 0xffff0000, v101
	v_pk_mul_f32 v[114:115], v[38:39], v[110:111]
	v_pk_mul_f32 v[112:113], v[36:37], v[108:109]
	v_lshlrev_b32_e32 v108, 16, v98
	v_and_b32_e32 v109, 0xffff0000, v98
	v_lshlrev_b32_e32 v110, 16, v99
	v_and_b32_e32 v111, 0xffff0000, v99
	v_pk_fma_f32 v[112:113], v[40:41], v[108:109], v[112:113]
	v_pk_fma_f32 v[114:115], v[42:43], v[110:111], v[114:115]
	v_lshlrev_b32_e32 v108, 16, v96
	v_and_b32_e32 v109, 0xffff0000, v96
	v_lshlrev_b32_e32 v110, 16, v97
	v_and_b32_e32 v111, 0xffff0000, v97
	v_pk_fma_f32 v[114:115], v[46:47], v[110:111], v[114:115]
	v_pk_fma_f32 v[112:113], v[44:45], v[108:109], v[112:113]
	v_lshlrev_b32_e32 v108, 16, v94
	v_and_b32_e32 v109, 0xffff0000, v94
	v_lshlrev_b32_e32 v110, 16, v95
	v_and_b32_e32 v111, 0xffff0000, v95
	v_pk_mul_f32 v[112:113], v[112:113], v[108:109]
	v_pk_mul_f32 v[114:115], v[114:115], v[110:111]
	v_lshlrev_b32_e32 v108, 16, v102
	v_and_b32_e32 v109, 0xffff0000, v102
	v_lshlrev_b32_e32 v110, 16, v103
	v_and_b32_e32 v111, 0xffff0000, v103
	v_pk_mul_f32 v[114:115], v[114:115], v[110:111]
	v_pk_mul_f32 v[112:113], v[112:113], v[108:109]
	s_nop 0
	v_cvt_pk_bf16_f32 v116, v112, v113
	v_cvt_pk_bf16_f32 v117, v114, v115
	global_store_dwordx2 v106, v[116:117], s[2:3]

; DI v2u pack4(f32x4 a) { v2u w; w.x = cvtpk(a[0], a[1]); w.y = cvtpk(a[2], a[3]); return w; }
; DI f32x4 unpack4(v2u w) { return (f32x4){bflo(w.x), bfhi(w.x), bflo(w.y), bfhi(w.y)}; }
; DI void unit_memattn(int u, const bf16* __restrict__ MQ, const bf16* __restrict__ MK, const bf16* __restrict__ MV, const bf16* __restrict__ G, bf16* __restrict__ MIX, const bf16* __restrict__ CB, const bf16* __restrict__ U, const float* __restrict__ convw, ...
;     ...
;     const int b = u >> 7, hm = (u >> 5) & 3, qb = u & 31;
;     const long goff0 = ((long)b * 256) * 256 + hm * 64;
;     v4u fk[4], fv[4], gv[4];
; #pragma unroll
;     for (int i = 0; i < 4; ++i) { const int id = tid + NT * i, j = id >> 3, ch = id & 7;
;         fk[i] = *(const v4u*)(MK + goff0 + (long)j * 256 + ch * 8); fv[i] = *(const v4u*)(MV + goff0 + (long)j * 256 + ch * 8);
;         gv[i] = *(const v4u*)(G + ((size_t)b * SEQ + qb * 256 + j) * D + 768 + hm * 64 + ch * 8); }
;     {   const int c4 = hm * 64 + (tid & 15) * 4;
;         const f32x4 w0 = *(const f32x4*)(convw + c4), w1 = *(const f32x4*)(convw + 256 + c4), w2 = *(const f32x4*)(convw + 512 + c4);
; #pragma unroll 4
;         for (int rl = tid >> 4; rl < 256; rl += NT / 16) { const size_t r2 = (size_t)b * SEQ + qb * 256 + rl; const int t = (int)(r2 & (SEQ - 1));
;             const f32x4 cb = unpack4(*(const v2u*)(CB + r2 * 256 + c4)), u0 = unpack4(*(const v2u*)(U + r2 * 256 + c4));
;             f32x4 u1 = (f32x4){0.f, 0.f, 0.f, 0.f}, u2 = u1;
;             if (t >= 1) u1 = unpack4(*(const v2u*)(U + (r2 - 1) * 256 + c4));
;             if (t >= 2) u2 = unpack4(*(const v2u*)(U + (r2 - 2) * 256 + c4));
;             const f32x4 gg = unpack4(*(const v2u*)(G + r2 * D + c4));
;             *(v2u*)(MIX + r2 * D + c4) = pack4(cb * (w0 * u2 + w1 * u1 + w2 * u0) * gg); }
.LBB0_646:
	s_and_b64 vcc, exec, s[2:3]
	s_cbranch_vccz .LBB0_645
	s_ashr_i32 s10, s12, 7
	s_lshl_b32 s0, s12, 1
	s_ashr_i32 s11, s10, 31
	s_and_b32 s2, s0, 0xc0
	s_lshl_b64 s[0:1], s[10:11], 17
	s_lshl_b32 s8, s2, 1
	s_or_b32 s0, s0, s8
	v_mov_b32_e32 v150, v182
	v_mov_b32_e32 v1, v0
	s_add_u32 s14, s64, s0
	s_addc_u32 s15, s65, s1
	v_lshlrev_b32_e32 v2, 3, v1
	v_and_b32_e32 v2, 56, v2
	s_add_u32 s0, s66, s0
	v_mov_b32_e32 v131, 0
	v_lshlrev_b32_e32 v130, 1, v2
	s_addc_u32 s1, s67, s1
	s_lshl_b32 s3, s12, 8
	v_lshl_add_u64 v[30:31], s[0:1], 0, v[130:131]
	s_lshl_b64 s[0:1], s[10:11], 13
	s_and_b32 s11, s3, 0x1f00
	v_ashrrev_i32_e32 v140, 3, v1
	s_or_b32 s12, s0, s11
	s_mov_b32 s13, s1
	v_ashrrev_i32_e32 v141, 31, v140
	v_lshlrev_b64 v[2:3], 9, v[140:141]
	v_lshl_add_u64 v[10:11], s[12:13], 0, v[140:141]
	v_add_u32_e32 v141, 0x200, v1
	v_ashrrev_i32_e32 v142, 3, v141
	v_ashrrev_i32_e32 v143, 31, v142
	v_lshl_add_u64 v[16:17], s[12:13], 0, v[142:143]
	v_lshlrev_b64 v[138:139], 11, v[10:11]
	v_lshlrev_b64 v[136:137], 11, v[16:17]
	s_mov_b32 s9, 0
	v_lshl_add_u64 v[10:11], s[24:25], 0, v[138:139]
	v_lshlrev_b64 v[14:15], 9, v[142:143]
	v_lshl_add_u64 v[16:17], s[24:25], 0, v[136:137]
	v_add_u32_e32 v143, 0x400, v1
	v_lshl_add_u64 v[26:27], s[14:15], 0, v[130:131]
	v_lshl_add_u64 v[10:11], v[10:11], 0, s[8:9]
	v_lshl_add_u64 v[16:17], v[16:17], 0, s[8:9]
	v_ashrrev_i32_e32 v144, 3, v143
	v_lshl_add_u64 v[4:5], v[26:27], 0, v[2:3]
	v_lshl_add_u64 v[6:7], v[30:31], 0, v[2:3]
	v_lshl_add_u64 v[10:11], v[10:11], 0, v[130:131]
	v_lshl_add_u64 v[12:13], v[26:27], 0, v[14:15]
	v_lshl_add_u64 v[14:15], v[30:31], 0, v[14:15]
	v_lshl_add_u64 v[18:19], v[16:17], 0, v[130:131]
	v_ashrrev_i32_e32 v145, 31, v144
	global_load_dwordx4 v[2:5], v[4:5], off
	s_nop 0
	global_load_dwordx4 v[6:9], v[6:7], off
	s_nop 0
	global_load_dwordx4 v[78:81], v[10:11], off offset:1536
	s_nop 0
	global_load_dwordx4 v[10:13], v[12:13], off
	s_nop 0
	global_load_dwordx4 v[14:17], v[14:15], off
	s_nop 0
	global_load_dwordx4 v[74:77], v[18:19], off offset:1536
	v_lshlrev_b64 v[18:19], 9, v[144:145]
	v_lshl_add_u64 v[28:29], s[12:13], 0, v[144:145]
	v_add_u32_e32 v145, 0x600, v1
	v_ashrrev_i32_e32 v146, 3, v145
	v_ashrrev_i32_e32 v147, 31, v146
	v_lshlrev_b64 v[32:33], 9, v[146:147]
	v_lshl_add_u64 v[20:21], v[26:27], 0, v[18:19]
	v_lshl_add_u64 v[22:23], v[30:31], 0, v[18:19]
	v_lshlrev_b64 v[134:135], 11, v[28:29]
	v_lshl_add_u64 v[26:27], v[26:27], 0, v[32:33]
	v_lshl_add_u64 v[30:31], v[30:31], 0, v[32:33]
	v_lshl_add_u64 v[32:33], s[12:13], 0, v[146:147]
	v_lshl_add_u64 v[28:29], s[24:25], 0, v[134:135]
	v_lshlrev_b64 v[132:133], 11, v[32:33]
	v_lshl_add_u64 v[28:29], v[28:29], 0, s[8:9]
	v_lshl_add_u64 v[32:33], s[24:25], 0, v[132:133]
	v_lshl_add_u64 v[28:29], v[28:29], 0, v[130:131]
	v_lshl_add_u64 v[32:33], v[32:33], 0, s[8:9]
	global_load_dwordx4 v[18:21], v[20:21], off
	s_nop 0
	global_load_dwordx4 v[22:25], v[22:23], off
	s_nop 0
	global_load_dwordx4 v[70:73], v[28:29], off offset:1536
	s_nop 0
	global_load_dwordx4 v[26:29], v[26:27], off
	v_lshl_add_u64 v[34:35], v[32:33], 0, v[130:131]
	global_load_dwordx4 v[30:33], v[30:31], off
	s_nop 0
	global_load_dwordx4 v[66:69], v[34:35], off offset:1536
	v_ashrrev_i32_e32 v60, 4, v1
	s_movk_i32 s3, 0x100
	v_cmp_gt_i32_e32 vcc, s3, v60
	s_and_saveexec_b64 s[12:13], vcc
	s_cbranch_execz .LBB0_675
	v_lshlrev_b32_e32 v107, 2, v1
	v_and_or_b32 v107, v107, 60, s2
	v_readlane_b32 s40, v247, 25
	v_readlane_b32 s41, v247, 26
	v_readlane_b32 s42, v247, 27
	v_readlane_b32 s43, v247, 28
	v_readlane_b32 s44, v247, 29
	v_readlane_b32 s45, v247, 30
	v_readlane_b32 s46, v247, 31
	v_readlane_b32 s47, v247, 32
	v_readlane_b32 s48, v247, 33
	v_readlane_b32 s49, v247, 34
	v_readlane_b32 s50, v247, 35
	v_readlane_b32 s51, v247, 36
	v_readlane_b32 s52, v247, 37
	v_readlane_b32 s53, v247, 38
	v_readlane_b32 s54, v247, 39
	v_readlane_b32 s55, v247, 40
	v_lshlrev_b32_e32 v103, 2, v107
	v_mov_b32_e32 v102, 0
	s_lshl_b32 s9, s10, 13
	s_or_b32 s9, s9, s11
	global_load_dwordx4 v[34:37], v103, s[44:45]
	global_load_dwordx4 v[38:41], v103, s[44:45] offset:1024
	global_load_dwordx4 v[42:45], v103, s[44:45] offset:2048
	s_lshl_b32 s0, s9, 9
	s_add_u32 s0, s0, 0x3400000
	s_add_u32 s0, s82, s0
	s_addc_u32 s1, s83, 0
	s_add_u32 s2, s0, 0xa00000
	s_addc_u32 s3, s1, 0
	s_lshl_b32 s16, s9, 11
	s_add_u32 s16, s16, 0x8800000
	s_add_u32 s16, s82, s16
	s_addc_u32 s17, s83, 0
	s_add_u32 s18, s16, 0x5800000
	s_addc_u32 s19, s17, 0
	v_lshlrev_b32_e32 v107, 1, v107
	v_add_u32_e32 v106, s11, v60
	v_lshl_add_u32 v103, v60, 9, v107
	v_lshl_add_u32 v104, v60, 11, v107
	v_mov_b32_e32 v105, v104
	global_load_dwordx2 v[46:47], v103, s[0:1]
	global_load_dwordx2 v[48:49], v103, s[2:3]
	global_load_dwordx2 v[50:51], v103, s[2:3] offset:-512
	global_load_dwordx2 v[52:53], v103, s[2:3] offset:-1024
	global_load_dwordx2 v[54:55], v104, s[16:17]
	v_add_u32_e32 v103, 0x4000, v103
	v_add_u32_e32 v104, 0x10000, v104
	global_load_dwordx2 v[56:57], v103, s[0:1]
	global_load_dwordx2 v[58:59], v103, s[2:3]
	global_load_dwordx2 v[60:61], v103, s[2:3] offset:-512
	global_load_dwordx2 v[62:63], v103, s[2:3] offset:-1024
	global_load_dwordx2 v[64:65], v104, s[16:17]
	v_add_u32_e32 v103, 0x4000, v103
	v_add_u32_e32 v104, 0x10000, v104
	global_load_dwordx2 v[82:83], v103, s[0:1]
	global_load_dwordx2 v[84:85], v103, s[2:3]
	global_load_dwordx2 v[86:87], v103, s[2:3] offset:-512
	global_load_dwordx2 v[88:89], v103, s[2:3] offset:-1024
	global_load_dwordx2 v[90:91], v104, s[16:17]
	v_add_u32_e32 v103, 0x4000, v103
	v_add_u32_e32 v104, 0x10000, v104
	global_load_dwordx2 v[92:93], v103, s[0:1]
	global_load_dwordx2 v[94:95], v103, s[2:3]
	global_load_dwordx2 v[96:97], v103, s[2:3] offset:-512
	global_load_dwordx2 v[98:99], v103, s[2:3] offset:-1024
	global_load_dwordx2 v[100:101], v104, s[16:17]
	v_add_u32_e32 v103, 0x4000, v103
	v_add_u32_e32 v104, 0x10000, v104
	s_waitcnt vmcnt(15)
; DI v2u pack4(f32x4 a) { v2u w; w.x = cvtpk(a[0], a[1]); w.y = cvtpk(a[2], a[3]); return w; }
; DI f32x4 unpack4(v2u w) { return (f32x4){bflo(w.x), bfhi(w.x), bflo(w.y), bfhi(w.y)}; }
; DI void unit_memattn(int u, const bf16* __restrict__ MQ, const bf16* __restrict__ MK, const bf16* __restrict__ MV, const bf16* __restrict__ G, bf16* __restrict__ MIX, const bf16* __restrict__ CB, const bf16* __restrict__ U, const float* __restrict__ convw, ...
;     ...
;         for (int rl = tid >> 4; rl < 256; rl += NT / 16) { const size_t r2 = (size_t)b * SEQ + qb * 256 + rl; const int t = (int)(r2 & (SEQ - 1));
;             const f32x4 cb = unpack4(*(const v2u*)(CB + r2 * 256 + c4)), u0 = unpack4(*(const v2u*)(U + r2 * 256 + c4));
;             f32x4 u1 = (f32x4){0.f, 0.f, 0.f, 0.f}, u2 = u1;
;             if (t >= 1) u1 = unpack4(*(const v2u*)(U + (r2 - 1) * 256 + c4));
;             if (t >= 2) u2 = unpack4(*(const v2u*)(U + (r2 - 2) * 256 + c4));
;             const f32x4 gg = unpack4(*(const v2u*)(G + r2 * D + c4));
;             *(v2u*)(MIX + r2 * D + c4) = pack4(cb * (w0 * u2 + w1 * u1 + w2 * u0) * gg); }
	v_cmp_ne_u32_e32 vcc, 0, v106
	s_nop 1
	v_cndmask_b32_e32 v50, v102, v50, vcc
	v_cndmask_b32_e32 v51, v102, v51, vcc
	v_cmp_lt_u32_e32 vcc, 1, v106
	s_nop 1
	v_cndmask_b32_e32 v52, v102, v52, vcc
	v_cndmask_b32_e32 v53, v102, v53, vcc
	v_lshlrev_b32_e32 v108, 16, v52
	v_and_b32_e32 v109, 0xffff0000, v52
	v_lshlrev_b32_e32 v110, 16, v53
	v_and_b32_e32 v111, 0xffff0000, v53
	v_pk_mul_f32 v[114:115], v[36:37], v[110:111]
	v_pk_mul_f32 v[112:113], v[34:35], v[108:109]
	v_lshlrev_b32_e32 v108, 16, v50
	v_and_b32_e32 v109, 0xffff0000, v50
	v_lshlrev_b32_e32 v110, 16, v51
	v_and_b32_e32 v111, 0xffff0000, v51
	v_pk_fma_f32 v[112:113], v[38:39], v[108:109], v[112:113]
	v_pk_fma_f32 v[114:115], v[40:41], v[110:111], v[114:115]
	v_lshlrev_b32_e32 v108, 16, v48
	v_and_b32_e32 v109, 0xffff0000, v48
	v_lshlrev_b32_e32 v110, 16, v49
	v_and_b32_e32 v111, 0xffff0000, v49
	v_pk_fma_f32 v[114:115], v[44:45], v[110:111], v[114:115]
	v_pk_fma_f32 v[112:113], v[42:43], v[108:109], v[112:113]
	v_lshlrev_b32_e32 v108, 16, v46
	v_and_b32_e32 v109, 0xffff0000, v46
	v_lshlrev_b32_e32 v110, 16, v47
	v_and_b32_e32 v111, 0xffff0000, v47
	v_pk_mul_f32 v[112:113], v[112:113], v[108:109]
	v_pk_mul_f32 v[114:115], v[114:115], v[110:111]
	v_lshlrev_b32_e32 v108, 16, v54
	v_and_b32_e32 v109, 0xffff0000, v54
	v_lshlrev_b32_e32 v110, 16, v55
	v_and_b32_e32 v111, 0xffff0000, v55
	v_pk_mul_f32 v[114:115], v[114:115], v[110:111]
	v_pk_mul_f32 v[112:113], v[112:113], v[108:109]
	s_nop 0
	v_cvt_pk_bf16_f32 v116, v112, v113
	v_cvt_pk_bf16_f32 v117, v114, v115
	global_load_dwordx2 v[46:47], v103, s[0:1]
	global_load_dwordx2 v[48:49], v103, s[2:3]
	global_load_dwordx2 v[50:51], v103, s[2:3] offset:-512
	global_load_dwordx2 v[52:53], v103, s[2:3] offset:-1024
	global_load_dwordx2 v[54:55], v104, s[16:17]
	v_add_u32_e32 v103, 0x4000, v103
	v_add_u32_e32 v104, 0x10000, v104
	global_store_dwordx2 v105, v[116:117], s[18:19]
	v_add_u32_e32 v105, 0x10000, v105
	s_waitcnt vmcnt(16)
	v_lshlrev_b32_e32 v108, 16, v62
	v_and_b32_e32 v109, 0xffff0000, v62
	v_lshlrev_b32_e32 v110, 16, v63
	v_and_b32_e32 v111, 0xffff0000, v63
	v_pk_mul_f32 v[114:115], v[36:37], v[110:111]
	v_pk_mul_f32 v[112:113], v[34:35], v[108:109]
	v_lshlrev_b32_e32 v108, 16, v60
	v_and_b32_e32 v109, 0xffff0000, v60
	v_lshlrev_b32_e32 v110, 16, v61
	v_and_b32_e32 v111, 0xffff0000, v61
	v_pk_fma_f32 v[112:113], v[38:39], v[108:109], v[112:113]
	v_pk_fma_f32 v[114:115], v[40:41], v[110:111], v[114:115]
	v_lshlrev_b32_e32 v108, 16, v58
	v_and_b32_e32 v109, 0xffff0000, v58
	v_lshlrev_b32_e32 v110, 16, v59
	v_and_b32_e32 v111, 0xffff0000, v59
	v_pk_fma_f32 v[114:115], v[44:45], v[110:111], v[114:115]
	v_pk_fma_f32 v[112:113], v[42:43], v[108:109], v[112:113]
	v_lshlrev_b32_e32 v108, 16, v56
	v_and_b32_e32 v109, 0xffff0000, v56
	v_lshlrev_b32_e32 v110, 16, v57
	v_and_b32_e32 v111, 0xffff0000, v57
	v_pk_mul_f32 v[112:113], v[112:113], v[108:109]
	v_pk_mul_f32 v[114:115], v[114:115], v[110:111]
	v_lshlrev_b32_e32 v108, 16, v64
	v_and_b32_e32 v109, 0xffff0000, v64
	v_lshlrev_b32_e32 v110, 16, v65
	v_and_b32_e32 v111, 0xffff0000, v65
	v_pk_mul_f32 v[114:115], v[114:115], v[110:111]
	v_pk_mul_f32 v[112:113], v[112:113], v[108:109]
	s_nop 0
	v_cvt_pk_bf16_f32 v116, v112, v113
	v_cvt_pk_bf16_f32 v117, v114, v115
	global_load_dwordx2 v[56:57], v103, s[0:1]
	global_load_dwordx2 v[58:59], v103, s[2:3]
	global_load_dwordx2 v[60:61], v103, s[2:3] offset:-512
	global_load_dwordx2 v[62:63], v103, s[2:3] offset:-1024
	global_load_dwordx2 v[64:65], v104, s[16:17]
	v_add_u32_e32 v103, 0x4000, v103
	v_add_u32_e32 v104, 0x10000, v104
	global_store_dwordx2 v105, v[116:117], s[18:19]
	v_add_u32_e32 v105, 0x10000, v105
	s_waitcnt vmcnt(17)
	v_lshlrev_b32_e32 v108, 16, v88
	v_and_b32_e32 v109, 0xffff0000, v88
	v_lshlrev_b32_e32 v110, 16, v89
	v_and_b32_e32 v111, 0xffff0000, v89
	v_pk_mul_f32 v[114:115], v[36:37], v[110:111]
	v_pk_mul_f32 v[112:113], v[34:35], v[108:109]
	v_lshlrev_b32_e32 v108, 16, v86
	v_and_b32_e32 v109, 0xffff0000, v86
	v_lshlrev_b32_e32 v110, 16, v87
	v_and_b32_e32 v111, 0xffff0000, v87
	v_pk_fma_f32 v[112:113], v[38:39], v[108:109], v[112:113]
	v_pk_fma_f32 v[114:115], v[40:41], v[110:111], v[114:115]
	v_lshlrev_b32_e32 v108, 16, v84
	v_and_b32_e32 v109, 0xffff0000, v84
	v_lshlrev_b32_e32 v110, 16, v85
	v_and_b32_e32 v111, 0xffff0000, v85
	v_pk_fma_f32 v[114:115], v[44:45], v[110:111], v[114:115]
	v_pk_fma_f32 v[112:113], v[42:43], v[108:109], v[112:113]
	v_lshlrev_b32_e32 v108, 16, v82
	v_and_b32_e32 v109, 0xffff0000, v82
	v_lshlrev_b32_e32 v110, 16, v83
	v_and_b32_e32 v111, 0xffff0000, v83
	v_pk_mul_f32 v[112:113], v[112:113], v[108:109]
	v_pk_mul_f32 v[114:115], v[114:115], v[110:111]
	v_lshlrev_b32_e32 v108, 16, v90
	v_and_b32_e32 v109, 0xffff0000, v90
	v_lshlrev_b32_e32 v110, 16, v91
	v_and_b32_e32 v111, 0xffff0000, v91
	v_pk_mul_f32 v[114:115], v[114:115], v[110:111]
	v_pk_mul_f32 v[112:113], v[112:113], v[108:109]
	s_nop 0
	v_cvt_pk_bf16_f32 v116, v112, v113
	v_cvt_pk_bf16_f32 v117, v114, v115
	global_load_dwordx2 v[82:83], v103, s[0:1]
	global_load_dwordx2 v[84:85], v103, s[2:3]
	global_load_dwordx2 v[86:87], v103, s[2:3] offset:-512
	global_load_dwordx2 v[88:89], v103, s[2:3] offset:-1024
	global_load_dwordx2 v[90:91], v104, s[16:17]
	v_add_u32_e32 v103, 0x4000, v103
	v_add_u32_e32 v104, 0x10000, v104
	global_store_dwordx2 v105, v[116:117], s[18:19]
	v_add_u32_e32 v105, 0x10000, v105
	s_waitcnt vmcnt(18)
; DI v2u pack4(f32x4 a) { v2u w; w.x = cvtpk(a[0], a[1]); w.y = cvtpk(a[2], a[3]); return w; }
; DI f32x4 unpack4(v2u w) { return (f32x4){bflo(w.x), bfhi(w.x), bflo(w.y), bfhi(w.y)}; }
; DI void unit_memattn(int u, const bf16* __restrict__ MQ, const bf16* __restrict__ MK, const bf16* __restrict__ MV, const bf16* __restrict__ G, bf16* __restrict__ MIX, const bf16* __restrict__ CB, const bf16* __restrict__ U, const float* __restrict__ convw, ...
;     ...
;         for (int rl = tid >> 4; rl < 256; rl += NT / 16) { const size_t r2 = (size_t)b * SEQ + qb * 256 + rl; const int t = (int)(r2 & (SEQ - 1));
;             const f32x4 cb = unpack4(*(const v2u*)(CB + r2 * 256 + c4)), u0 = unpack4(*(const v2u*)(U + r2 * 256 + c4));
;             f32x4 u1 = (f32x4){0.f, 0.f, 0.f, 0.f}, u2 = u1;
;             if (t >= 1) u1 = unpack4(*(const v2u*)(U + (r2 - 1) * 256 + c4));
;             if (t >= 2) u2 = unpack4(*(const v2u*)(U + (r2 - 2) * 256 + c4));
;             const f32x4 gg = unpack4(*(const v2u*)(G + r2 * D + c4));
;             *(v2u*)(MIX + r2 * D + c4) = pack4(cb * (w0 * u2 + w1 * u1 + w2 * u0) * gg); }
	v_lshlrev_b32_e32 v108, 16, v98
	v_and_b32_e32 v109, 0xffff0000, v98
	v_lshlrev_b32_e32 v110, 16, v99
	v_and_b32_e32 v111, 0xffff0000, v99
	v_pk_mul_f32 v[114:115], v[36:37], v[110:111]
	v_pk_mul_f32 v[112:113], v[34:35], v[108:109]
	v_lshlrev_b32_e32 v108, 16, v96
	v_and_b32_e32 v109, 0xffff0000, v96
	v_lshlrev_b32_e32 v110, 16, v97
	v_and_b32_e32 v111, 0xffff0000, v97
	v_pk_fma_f32 v[112:113], v[38:39], v[108:109], v[112:113]
	v_pk_fma_f32 v[114:115], v[40:41], v[110:111], v[114:115]
	v_lshlrev_b32_e32 v108, 16, v94
	v_and_b32_e32 v109, 0xffff0000, v94
	v_lshlrev_b32_e32 v110, 16, v95
	v_and_b32_e32 v111, 0xffff0000, v95
	v_pk_fma_f32 v[114:115], v[44:45], v[110:111], v[114:115]
	v_pk_fma_f32 v[112:113], v[42:43], v[108:109], v[112:113]
	v_lshlrev_b32_e32 v108, 16, v92
	v_and_b32_e32 v109, 0xffff0000, v92
	v_lshlrev_b32_e32 v110, 16, v93
	v_and_b32_e32 v111, 0xffff0000, v93
	v_pk_mul_f32 v[112:113], v[112:113], v[108:109]
	v_pk_mul_f32 v[114:115], v[114:115], v[110:111]
	v_lshlrev_b32_e32 v108, 16, v100
	v_and_b32_e32 v109, 0xffff0000, v100
	v_lshlrev_b32_e32 v110, 16, v101
	v_and_b32_e32 v111, 0xffff0000, v101
	v_pk_mul_f32 v[114:115], v[114:115], v[110:111]
	v_pk_mul_f32 v[112:113], v[112:113], v[108:109]
	s_nop 0
	v_cvt_pk_bf16_f32 v116, v112, v113
	v_cvt_pk_bf16_f32 v117, v114, v115
	global_load_dwordx2 v[92:93], v103, s[0:1]
	global_load_dwordx2 v[94:95], v103, s[2:3]
	global_load_dwordx2 v[96:97], v103, s[2:3] offset:-512
	global_load_dwordx2 v[98:99], v103, s[2:3] offset:-1024
	global_load_dwordx2 v[100:101], v104, s[16:17]
	global_store_dwordx2 v105, v[116:117], s[18:19]
	v_add_u32_e32 v105, 0x10000, v105
	s_waitcnt vmcnt(19)
	v_lshlrev_b32_e32 v108, 16, v52
	v_and_b32_e32 v109, 0xffff0000, v52
	v_lshlrev_b32_e32 v110, 16, v53
	v_and_b32_e32 v111, 0xffff0000, v53
	v_pk_mul_f32 v[114:115], v[36:37], v[110:111]
	v_pk_mul_f32 v[112:113], v[34:35], v[108:109]
	v_lshlrev_b32_e32 v108, 16, v50
	v_and_b32_e32 v109, 0xffff0000, v50
	v_lshlrev_b32_e32 v110, 16, v51
	v_and_b32_e32 v111, 0xffff0000, v51
	v_pk_fma_f32 v[112:113], v[38:39], v[108:109], v[112:113]
	v_pk_fma_f32 v[114:115], v[40:41], v[110:111], v[114:115]
	v_lshlrev_b32_e32 v108, 16, v48
	v_and_b32_e32 v109, 0xffff0000, v48
	v_lshlrev_b32_e32 v110, 16, v49
	v_and_b32_e32 v111, 0xffff0000, v49
	v_pk_fma_f32 v[114:115], v[44:45], v[110:111], v[114:115]
	v_pk_fma_f32 v[112:113], v[42:43], v[108:109], v[112:113]
	v_lshlrev_b32_e32 v108, 16, v46
	v_and_b32_e32 v109, 0xffff0000, v46
	v_lshlrev_b32_e32 v110, 16, v47
	v_and_b32_e32 v111, 0xffff0000, v47
	v_pk_mul_f32 v[112:113], v[112:113], v[108:109]
	v_pk_mul_f32 v[114:115], v[114:115], v[110:111]
	v_lshlrev_b32_e32 v108, 16, v54
	v_and_b32_e32 v109, 0xffff0000, v54
	v_lshlrev_b32_e32 v110, 16, v55
	v_and_b32_e32 v111, 0xffff0000, v55
	v_pk_mul_f32 v[114:115], v[114:115], v[110:111]
	v_pk_mul_f32 v[112:113], v[112:113], v[108:109]
	s_nop 0
	v_cvt_pk_bf16_f32 v116, v112, v113
	v_cvt_pk_bf16_f32 v117, v114, v115
	global_store_dwordx2 v105, v[116:117], s[18:19]
	v_add_u32_e32 v105, 0x10000, v105
	s_waitcnt vmcnt(14)
; DI v2u pack4(f32x4 a) { v2u w; w.x = cvtpk(a[0], a[1]); w.y = cvtpk(a[2], a[3]); return w; }
; DI f32x4 unpack4(v2u w) { return (f32x4){bflo(w.x), bfhi(w.x), bflo(w.y), bfhi(w.y)}; }
; DI void unit_memattn(int u, const bf16* __restrict__ MQ, const bf16* __restrict__ MK, const bf16* __restrict__ MV, const bf16* __restrict__ G, bf16* __restrict__ MIX, const bf16* __restrict__ CB, const bf16* __restrict__ U, const float* __restrict__ convw, ...
;     ...
;         for (int rl = tid >> 4; rl < 256; rl += NT / 16) { const size_t r2 = (size_t)b * SEQ + qb * 256 + rl; const int t = (int)(r2 & (SEQ - 1));
;             const f32x4 cb = unpack4(*(const v2u*)(CB + r2 * 256 + c4)), u0 = unpack4(*(const v2u*)(U + r2 * 256 + c4));
;             f32x4 u1 = (f32x4){0.f, 0.f, 0.f, 0.f}, u2 = u1;
;             if (t >= 1) u1 = unpack4(*(const v2u*)(U + (r2 - 1) * 256 + c4));
;             if (t >= 2) u2 = unpack4(*(const v2u*)(U + (r2 - 2) * 256 + c4));
;             const f32x4 gg = unpack4(*(const v2u*)(G + r2 * D + c4));
;             *(v2u*)(MIX + r2 * D + c4) = pack4(cb * (w0 * u2 + w1 * u1 + w2 * u0) * gg); }
	v_lshlrev_b32_e32 v108, 16, v62
	v_and_b32_e32 v109, 0xffff0000, v62
	v_lshlrev_b32_e32 v110, 16, v63
	v_and_b32_e32 v111, 0xffff0000, v63
	v_pk_mul_f32 v[114:115], v[36:37], v[110:111]
	v_pk_mul_f32 v[112:113], v[34:35], v[108:109]
	v_lshlrev_b32_e32 v108, 16, v60
	v_and_b32_e32 v109, 0xffff0000, v60
	v_lshlrev_b32_e32 v110, 16, v61
	v_and_b32_e32 v111, 0xffff0000, v61
	v_pk_fma_f32 v[112:113], v[38:39], v[108:109], v[112:113]
	v_pk_fma_f32 v[114:115], v[40:41], v[110:111], v[114:115]
	v_lshlrev_b32_e32 v108, 16, v58
	v_and_b32_e32 v109, 0xffff0000, v58
	v_lshlrev_b32_e32 v110, 16, v59
	v_and_b32_e32 v111, 0xffff0000, v59
	v_pk_fma_f32 v[114:115], v[44:45], v[110:111], v[114:115]
	v_pk_fma_f32 v[112:113], v[42:43], v[108:109], v[112:113]
	v_lshlrev_b32_e32 v108, 16, v56
	v_and_b32_e32 v109, 0xffff0000, v56
	v_lshlrev_b32_e32 v110, 16, v57
	v_and_b32_e32 v111, 0xffff0000, v57
	v_pk_mul_f32 v[112:113], v[112:113], v[108:109]
	v_pk_mul_f32 v[114:115], v[114:115], v[110:111]
	v_lshlrev_b32_e32 v108, 16, v64
	v_and_b32_e32 v109, 0xffff0000, v64
	v_lshlrev_b32_e32 v110, 16, v65
	v_and_b32_e32 v111, 0xffff0000, v65
	v_pk_mul_f32 v[114:115], v[114:115], v[110:111]
	v_pk_mul_f32 v[112:113], v[112:113], v[108:109]
	s_nop 0
	v_cvt_pk_bf16_f32 v116, v112, v113
	v_cvt_pk_bf16_f32 v117, v114, v115
	global_store_dwordx2 v105, v[116:117], s[18:19]
	v_add_u32_e32 v105, 0x10000, v105
	s_waitcnt vmcnt(9)
	v_lshlrev_b32_e32 v108, 16, v88
	v_and_b32_e32 v109, 0xffff0000, v88
	v_lshlrev_b32_e32 v110, 16, v89
	v_and_b32_e32 v111, 0xffff0000, v89
	v_pk_mul_f32 v[114:115], v[36:37], v[110:111]
	v_pk_mul_f32 v[112:113], v[34:35], v[108:109]
	v_lshlrev_b32_e32 v108, 16, v86
	v_and_b32_e32 v109, 0xffff0000, v86
	v_lshlrev_b32_e32 v110, 16, v87
	v_and_b32_e32 v111, 0xffff0000, v87
	v_pk_fma_f32 v[112:113], v[38:39], v[108:109], v[112:113]
	v_pk_fma_f32 v[114:115], v[40:41], v[110:111], v[114:115]
	v_lshlrev_b32_e32 v108, 16, v84
	v_and_b32_e32 v109, 0xffff0000, v84
	v_lshlrev_b32_e32 v110, 16, v85
	v_and_b32_e32 v111, 0xffff0000, v85
	v_pk_fma_f32 v[114:115], v[44:45], v[110:111], v[114:115]
	v_pk_fma_f32 v[112:113], v[42:43], v[108:109], v[112:113]
	v_lshlrev_b32_e32 v108, 16, v82
	v_and_b32_e32 v109, 0xffff0000, v82
	v_lshlrev_b32_e32 v110, 16, v83
	v_and_b32_e32 v111, 0xffff0000, v83
	v_pk_mul_f32 v[112:113], v[112:113], v[108:109]
	v_pk_mul_f32 v[114:115], v[114:115], v[110:111]
	v_lshlrev_b32_e32 v108, 16, v90
	v_and_b32_e32 v109, 0xffff0000, v90
	v_lshlrev_b32_e32 v110, 16, v91
	v_and_b32_e32 v111, 0xffff0000, v91
	v_pk_mul_f32 v[114:115], v[114:115], v[110:111]
	v_pk_mul_f32 v[112:113], v[112:113], v[108:109]
	s_nop 0
	v_cvt_pk_bf16_f32 v116, v112, v113
	v_cvt_pk_bf16_f32 v117, v114, v115
	global_store_dwordx2 v105, v[116:117], s[18:19]
	v_add_u32_e32 v105, 0x10000, v105
	s_waitcnt vmcnt(4)
	v_lshlrev_b32_e32 v108, 16, v98
	v_and_b32_e32 v109, 0xffff0000, v98
	v_lshlrev_b32_e32 v110, 16, v99
	v_and_b32_e32 v111, 0xffff0000, v99
	v_pk_mul_f32 v[114:115], v[36:37], v[110:111]
	v_pk_mul_f32 v[112:113], v[34:35], v[108:109]
	v_lshlrev_b32_e32 v108, 16, v96
	v_and_b32_e32 v109, 0xffff0000, v96
	v_lshlrev_b32_e32 v110, 16, v97
	v_and_b32_e32 v111, 0xffff0000, v97
	v_pk_fma_f32 v[112:113], v[38:39], v[108:109], v[112:113]
	v_pk_fma_f32 v[114:115], v[40:41], v[110:111], v[114:115]
	v_lshlrev_b32_e32 v108, 16, v94
	v_and_b32_e32 v109, 0xffff0000, v94
	v_lshlrev_b32_e32 v110, 16, v95
	v_and_b32_e32 v111, 0xffff0000, v95
	v_pk_fma_f32 v[114:115], v[44:45], v[110:111], v[114:115]
	v_pk_fma_f32 v[112:113], v[42:43], v[108:109], v[112:113]
	v_lshlrev_b32_e32 v108, 16, v92
	v_and_b32_e32 v109, 0xffff0000, v92
	v_lshlrev_b32_e32 v110, 16, v93
	v_and_b32_e32 v111, 0xffff0000, v93
	v_pk_mul_f32 v[112:113], v[112:113], v[108:109]
	v_pk_mul_f32 v[114:115], v[114:115], v[110:111]
	v_lshlrev_b32_e32 v108, 16, v100
	v_and_b32_e32 v109, 0xffff0000, v100
	v_lshlrev_b32_e32 v110, 16, v101
	v_and_b32_e32 v111, 0xffff0000, v101
	v_pk_mul_f32 v[114:115], v[114:115], v[110:111]
	v_pk_mul_f32 v[112:113], v[112:113], v[108:109]
	s_nop 0
	v_cvt_pk_bf16_f32 v116, v112, v113
	v_cvt_pk_bf16_f32 v117, v114, v115
	global_store_dwordx2 v105, v[116:117], s[18:19]
